# FFN-up phase: the two wave halves no longer align before the epilogue (leading half starts its epilogue while the trailing half runs its last MFMA block); barrier kept only before the last unit's epil
# baseline (speedup 1.0000x reference)
.LBB0_1190:
	s_add_u32 s67, s82, 0xfff80080
	s_addc_u32 s84, s83, -1
	s_add_i32 s89, 0, 0x10000
	s_cmp_eq_u32 s88, 28
	s_cselect_b32 s87, s71, s84
	s_cselect_b32 s86, s72, s67
	s_cselect_b32 s85, s23, s81
	s_cselect_b32 s84, s73, s75
	s_add_i32 s67, 0, 0x14000
	v_add_u32_e32 v76, s89, v192
	v_add_u32_e32 v156, s67, v192
	ds_read_b128 v[64:67], v76
	ds_read_b128 v[68:71], v76 offset:1024
	ds_read_b128 v[72:75], v76 offset:2048
	ds_read_b128 v[76:79], v76 offset:3072
	ds_read_b128 v[80:83], v156
	ds_read_b128 v[116:119], v156 offset:1024
	ds_read_b128 v[152:155], v156 offset:2048
	ds_read_b128 v[156:159], v156 offset:3072
	s_add_i32 m0, s28, 0xc000
	ds_read_b128 v[160:163], v193
	ds_read_b128 v[164:167], v193 offset:1024
	ds_read_b128 v[168:171], v193 offset:2048
	ds_read_b128 v[172:175], v193 offset:3072
	ds_read_b128 v[194:197], v193 offset:4096
	ds_read_b128 v[198:201], v193 offset:5120
	ds_read_b128 v[202:205], v193 offset:6144
	ds_read_b128 v[206:209], v193 offset:7168
	global_load_lds_dwordx4 v186, s[82:83]
	s_add_i32 m0, s28, 0xe000
	s_nop 0
	global_load_lds_dwordx4 v188, s[82:83]
	s_waitcnt vmcnt(8)
	s_waitcnt lgkmcnt(0)
	s_barrier
	s_waitcnt lgkmcnt(0)
	v_mfma_f32_16x16x32_bf16 v[148:151], v[64:67], v[160:163], v[148:151]
	v_mfma_f32_16x16x32_bf16 v[148:151], v[68:71], v[164:167], v[148:151]
	v_mfma_f32_16x16x32_bf16 v[140:143], v[80:83], v[160:163], v[140:143]
	v_mfma_f32_16x16x32_bf16 v[140:143], v[116:119], v[164:167], v[140:143]
	v_mfma_f32_16x16x32_bf16 v[144:147], v[72:75], v[160:163], v[144:147]
	v_mfma_f32_16x16x32_bf16 v[144:147], v[76:79], v[164:167], v[144:147]
	v_mfma_f32_16x16x32_bf16 v[136:139], v[152:155], v[160:163], v[136:139]
	v_mfma_f32_16x16x32_bf16 v[136:139], v[156:159], v[164:167], v[136:139]
	v_mfma_f32_16x16x32_bf16 v[132:135], v[64:67], v[168:171], v[132:135]
	v_mfma_f32_16x16x32_bf16 v[132:135], v[68:71], v[172:175], v[132:135]
	v_mfma_f32_16x16x32_bf16 v[124:127], v[80:83], v[168:171], v[124:127]
	v_mfma_f32_16x16x32_bf16 v[124:127], v[116:119], v[172:175], v[124:127]
	v_mfma_f32_16x16x32_bf16 v[128:131], v[72:75], v[168:171], v[128:131]
	v_mfma_f32_16x16x32_bf16 v[128:131], v[76:79], v[172:175], v[128:131]
	v_mfma_f32_16x16x32_bf16 v[120:123], v[152:155], v[168:171], v[120:123]
	v_mfma_f32_16x16x32_bf16 v[120:123], v[156:159], v[172:175], v[120:123]
	v_mfma_f32_16x16x32_bf16 v[112:115], v[64:67], v[194:197], v[112:115]
	v_mfma_f32_16x16x32_bf16 v[112:115], v[68:71], v[198:201], v[112:115]
	v_mfma_f32_16x16x32_bf16 v[104:107], v[80:83], v[194:197], v[104:107]
	v_mfma_f32_16x16x32_bf16 v[104:107], v[116:119], v[198:201], v[104:107]
	v_mfma_f32_16x16x32_bf16 v[108:111], v[72:75], v[194:197], v[108:111]
	v_mfma_f32_16x16x32_bf16 v[108:111], v[76:79], v[198:201], v[108:111]
	v_mfma_f32_16x16x32_bf16 v[100:103], v[152:155], v[194:197], v[100:103]
	v_mfma_f32_16x16x32_bf16 v[100:103], v[156:159], v[198:201], v[100:103]
	v_mfma_f32_16x16x32_bf16 v[96:99], v[64:67], v[202:205], v[96:99]
	v_mfma_f32_16x16x32_bf16 v[96:99], v[68:71], v[206:209], v[96:99]
	v_mfma_f32_16x16x32_bf16 v[88:91], v[80:83], v[202:205], v[88:91]
	v_mfma_f32_16x16x32_bf16 v[88:91], v[116:119], v[206:209], v[88:91]
	v_mfma_f32_16x16x32_bf16 v[92:95], v[72:75], v[202:205], v[92:95]
	v_mfma_f32_16x16x32_bf16 v[92:95], v[76:79], v[206:209], v[92:95]
	v_mfma_f32_16x16x32_bf16 v[84:87], v[152:155], v[202:205], v[84:87]
	v_mfma_f32_16x16x32_bf16 v[84:87], v[156:159], v[206:209], v[84:87]
	s_barrier
	s_add_i32 s89, s89, s24
	s_mov_b32 m0, s89
	ds_read_b128 v[160:163], v193 offset:16384
	ds_read_b128 v[164:167], v193 offset:17408
	ds_read_b128 v[168:171], v193 offset:18432
	ds_read_b128 v[172:175], v193 offset:19456
	ds_read_b128 v[194:197], v193 offset:20480
	ds_read_b128 v[198:201], v193 offset:21504
	ds_read_b128 v[202:205], v193 offset:22528
	ds_read_b128 v[206:209], v193 offset:23552
	global_load_lds_dwordx4 v180, s[84:85]
	s_add_i32 m0, s89, 0x2000
	s_add_u32 s90, s84, 0x80000
	s_addc_u32 s91, s85, 0
	s_add_i32 s67, s67, s24
	global_load_lds_dwordx4 v176, s[84:85]
	s_mov_b32 m0, s67
	s_nop 0
	global_load_lds_dwordx4 v180, s[90:91]
	s_add_i32 m0, s67, 0x2000
	s_nop 0
	global_load_lds_dwordx4 v176, s[90:91]
	s_mov_b32 m0, s28
	s_nop 0
	global_load_lds_dwordx4 v182, s[86:87]
	s_mov_b32 m0, s29
	s_nop 0
	global_load_lds_dwordx4 v178, s[86:87]
	s_waitcnt vmcnt(8)
	s_waitcnt lgkmcnt(0)
	s_barrier
	s_waitcnt lgkmcnt(0)
	v_mfma_f32_16x16x32_bf16 v[60:63], v[64:67], v[160:163], v[60:63]
	v_mfma_f32_16x16x32_bf16 v[60:63], v[68:71], v[164:167], v[60:63]
	v_mfma_f32_16x16x32_bf16 v[52:55], v[80:83], v[160:163], v[52:55]
	v_mfma_f32_16x16x32_bf16 v[52:55], v[116:119], v[164:167], v[52:55]
	v_mfma_f32_16x16x32_bf16 v[56:59], v[72:75], v[160:163], v[56:59]
	v_mfma_f32_16x16x32_bf16 v[56:59], v[76:79], v[164:167], v[56:59]
	v_mfma_f32_16x16x32_bf16 v[48:51], v[152:155], v[160:163], v[48:51]
	v_mfma_f32_16x16x32_bf16 v[48:51], v[156:159], v[164:167], v[48:51]
	v_mfma_f32_16x16x32_bf16 v[44:47], v[64:67], v[168:171], v[44:47]
	v_mfma_f32_16x16x32_bf16 v[44:47], v[68:71], v[172:175], v[44:47]
	v_mfma_f32_16x16x32_bf16 v[36:39], v[80:83], v[168:171], v[36:39]
	v_mfma_f32_16x16x32_bf16 v[36:39], v[116:119], v[172:175], v[36:39]
	v_mfma_f32_16x16x32_bf16 v[40:43], v[72:75], v[168:171], v[40:43]
	v_mfma_f32_16x16x32_bf16 v[40:43], v[76:79], v[172:175], v[40:43]
	v_mfma_f32_16x16x32_bf16 v[32:35], v[152:155], v[168:171], v[32:35]
	v_mfma_f32_16x16x32_bf16 v[32:35], v[156:159], v[172:175], v[32:35]
	v_mfma_f32_16x16x32_bf16 v[28:31], v[64:67], v[194:197], v[28:31]
	v_mfma_f32_16x16x32_bf16 v[28:31], v[68:71], v[198:201], v[28:31]
	v_mfma_f32_16x16x32_bf16 v[20:23], v[80:83], v[194:197], v[20:23]
	v_mfma_f32_16x16x32_bf16 v[20:23], v[116:119], v[198:201], v[20:23]
	v_mfma_f32_16x16x32_bf16 v[24:27], v[72:75], v[194:197], v[24:27]
	v_mfma_f32_16x16x32_bf16 v[24:27], v[76:79], v[198:201], v[24:27]
	v_mfma_f32_16x16x32_bf16 v[16:19], v[152:155], v[194:197], v[16:19]
	v_mfma_f32_16x16x32_bf16 v[16:19], v[156:159], v[198:201], v[16:19]
	v_mfma_f32_16x16x32_bf16 v[12:15], v[64:67], v[202:205], v[12:15]
	v_mfma_f32_16x16x32_bf16 v[12:15], v[68:71], v[206:209], v[12:15]
	v_mfma_f32_16x16x32_bf16 v[4:7], v[80:83], v[202:205], v[4:7]
	v_mfma_f32_16x16x32_bf16 v[4:7], v[116:119], v[206:209], v[4:7]
	v_mfma_f32_16x16x32_bf16 v[8:11], v[72:75], v[202:205], v[8:11]
	v_mfma_f32_16x16x32_bf16 v[8:11], v[76:79], v[206:209], v[8:11]
	v_mfma_f32_16x16x32_bf16 v[0:3], v[152:155], v[202:205], v[0:3]
	v_mfma_f32_16x16x32_bf16 v[0:3], v[156:159], v[206:209], v[0:3]
	s_barrier
	s_add_i32 s67, 0, 0x18000
	s_add_i32 s89, 0, 0x1c000
	v_add_u32_e32 v76, s67, v192
	v_add_u32_e32 v156, s89, v192
	ds_read_b128 v[64:67], v76
	ds_read_b128 v[68:71], v76 offset:1024
	ds_read_b128 v[72:75], v76 offset:2048
	ds_read_b128 v[76:79], v76 offset:3072
	ds_read_b128 v[80:83], v156
	ds_read_b128 v[116:119], v156 offset:1024
	ds_read_b128 v[152:155], v156 offset:2048
	ds_read_b128 v[156:159], v156 offset:3072
	s_add_u32 s86, s86, 0x80000
	s_addc_u32 s87, s87, 0
	s_mov_b32 m0, s34
	ds_read_b128 v[160:163], v193 offset:32768
	ds_read_b128 v[164:167], v193 offset:33792
	ds_read_b128 v[168:171], v193 offset:34816
	ds_read_b128 v[172:175], v193 offset:35840
	ds_read_b128 v[194:197], v193 offset:36864
	ds_read_b128 v[198:201], v193 offset:37888
	ds_read_b128 v[202:205], v193 offset:38912
	ds_read_b128 v[206:209], v193 offset:39936
	global_load_lds_dwordx4 v182, s[86:87]
	s_mov_b32 m0, s35
	s_nop 0
	global_load_lds_dwordx4 v178, s[86:87]
	s_waitcnt vmcnt(8)
	s_waitcnt lgkmcnt(0)
	s_barrier
	s_waitcnt lgkmcnt(0)
	v_mfma_f32_16x16x32_bf16 v[148:151], v[64:67], v[160:163], v[148:151]
	v_mfma_f32_16x16x32_bf16 v[148:151], v[68:71], v[164:167], v[148:151]
	v_mfma_f32_16x16x32_bf16 v[140:143], v[80:83], v[160:163], v[140:143]
	v_mfma_f32_16x16x32_bf16 v[140:143], v[116:119], v[164:167], v[140:143]
	v_mfma_f32_16x16x32_bf16 v[144:147], v[72:75], v[160:163], v[144:147]
	v_mfma_f32_16x16x32_bf16 v[144:147], v[76:79], v[164:167], v[144:147]
	v_mfma_f32_16x16x32_bf16 v[136:139], v[152:155], v[160:163], v[136:139]
	v_mfma_f32_16x16x32_bf16 v[136:139], v[156:159], v[164:167], v[136:139]
	v_mfma_f32_16x16x32_bf16 v[132:135], v[64:67], v[168:171], v[132:135]
	v_mfma_f32_16x16x32_bf16 v[132:135], v[68:71], v[172:175], v[132:135]
	v_mfma_f32_16x16x32_bf16 v[124:127], v[80:83], v[168:171], v[124:127]
	v_mfma_f32_16x16x32_bf16 v[124:127], v[116:119], v[172:175], v[124:127]
	v_mfma_f32_16x16x32_bf16 v[128:131], v[72:75], v[168:171], v[128:131]
	v_mfma_f32_16x16x32_bf16 v[128:131], v[76:79], v[172:175], v[128:131]
	v_mfma_f32_16x16x32_bf16 v[120:123], v[152:155], v[168:171], v[120:123]
	v_mfma_f32_16x16x32_bf16 v[120:123], v[156:159], v[172:175], v[120:123]
	v_mfma_f32_16x16x32_bf16 v[112:115], v[64:67], v[194:197], v[112:115]
	v_mfma_f32_16x16x32_bf16 v[112:115], v[68:71], v[198:201], v[112:115]
	v_mfma_f32_16x16x32_bf16 v[104:107], v[80:83], v[194:197], v[104:107]
	v_mfma_f32_16x16x32_bf16 v[104:107], v[116:119], v[198:201], v[104:107]
	v_mfma_f32_16x16x32_bf16 v[108:111], v[72:75], v[194:197], v[108:111]
	v_mfma_f32_16x16x32_bf16 v[108:111], v[76:79], v[198:201], v[108:111]
	v_mfma_f32_16x16x32_bf16 v[100:103], v[152:155], v[194:197], v[100:103]
	v_mfma_f32_16x16x32_bf16 v[100:103], v[156:159], v[198:201], v[100:103]
	v_mfma_f32_16x16x32_bf16 v[96:99], v[64:67], v[202:205], v[96:99]
	v_mfma_f32_16x16x32_bf16 v[96:99], v[68:71], v[206:209], v[96:99]
	v_mfma_f32_16x16x32_bf16 v[88:91], v[80:83], v[202:205], v[88:91]
	v_mfma_f32_16x16x32_bf16 v[88:91], v[116:119], v[206:209], v[88:91]
	v_mfma_f32_16x16x32_bf16 v[92:95], v[72:75], v[202:205], v[92:95]
	v_mfma_f32_16x16x32_bf16 v[92:95], v[76:79], v[206:209], v[92:95]
	v_mfma_f32_16x16x32_bf16 v[84:87], v[152:155], v[202:205], v[84:87]
	v_mfma_f32_16x16x32_bf16 v[84:87], v[156:159], v[206:209], v[84:87]
	s_barrier
	s_add_i32 s67, s67, s24
	s_add_u32 s98, s84, 0x80
	s_addc_u32 s99, s85, 0
	s_mov_b32 m0, s67
	ds_read_b128 v[160:163], v193 offset:49152
	ds_read_b128 v[164:167], v193 offset:50176
	ds_read_b128 v[168:171], v193 offset:51200
	ds_read_b128 v[172:175], v193 offset:52224
	ds_read_b128 v[194:197], v193 offset:53248
	ds_read_b128 v[198:201], v193 offset:54272
	ds_read_b128 v[202:205], v193 offset:55296
	ds_read_b128 v[206:209], v193 offset:56320
	global_load_lds_dwordx4 v180, s[98:99]
	s_add_i32 m0, s67, 0x2000
	s_add_u32 s84, s84, 0x80080
	s_addc_u32 s85, s85, 0
	s_add_i32 s67, s89, s24
	global_load_lds_dwordx4 v176, s[98:99]
	s_mov_b32 m0, s67
	s_nop 0
	global_load_lds_dwordx4 v180, s[84:85]
	s_add_i32 m0, s67, 0x2000
	s_nop 0
	global_load_lds_dwordx4 v176, s[84:85]
	s_add_u32 s98, s86, 0xfff80080
	s_addc_u32 s99, s87, -1
	s_mov_b32 m0, s53
	s_nop 0
	global_load_lds_dwordx4 v182, s[98:99]
	s_mov_b32 m0, s54
	s_nop 0
	global_load_lds_dwordx4 v178, s[98:99]
	s_waitcnt vmcnt(8)
	s_waitcnt lgkmcnt(0)
	s_barrier
	s_waitcnt lgkmcnt(0)
	v_mfma_f32_16x16x32_bf16 v[60:63], v[64:67], v[160:163], v[60:63]
	v_mfma_f32_16x16x32_bf16 v[60:63], v[68:71], v[164:167], v[60:63]
	v_mfma_f32_16x16x32_bf16 v[52:55], v[80:83], v[160:163], v[52:55]
	v_mfma_f32_16x16x32_bf16 v[52:55], v[116:119], v[164:167], v[52:55]
	v_mfma_f32_16x16x32_bf16 v[56:59], v[72:75], v[160:163], v[56:59]
	v_mfma_f32_16x16x32_bf16 v[56:59], v[76:79], v[164:167], v[56:59]
	v_mfma_f32_16x16x32_bf16 v[48:51], v[152:155], v[160:163], v[48:51]
	v_mfma_f32_16x16x32_bf16 v[48:51], v[156:159], v[164:167], v[48:51]
	v_mfma_f32_16x16x32_bf16 v[44:47], v[64:67], v[168:171], v[44:47]
	v_mfma_f32_16x16x32_bf16 v[44:47], v[68:71], v[172:175], v[44:47]
	v_mfma_f32_16x16x32_bf16 v[36:39], v[80:83], v[168:171], v[36:39]
	v_mfma_f32_16x16x32_bf16 v[36:39], v[116:119], v[172:175], v[36:39]
	v_mfma_f32_16x16x32_bf16 v[40:43], v[72:75], v[168:171], v[40:43]
	v_mfma_f32_16x16x32_bf16 v[40:43], v[76:79], v[172:175], v[40:43]
	v_mfma_f32_16x16x32_bf16 v[32:35], v[152:155], v[168:171], v[32:35]
	v_mfma_f32_16x16x32_bf16 v[32:35], v[156:159], v[172:175], v[32:35]
	v_mfma_f32_16x16x32_bf16 v[28:31], v[64:67], v[194:197], v[28:31]
	v_mfma_f32_16x16x32_bf16 v[28:31], v[68:71], v[198:201], v[28:31]
	v_mfma_f32_16x16x32_bf16 v[20:23], v[80:83], v[194:197], v[20:23]
	v_mfma_f32_16x16x32_bf16 v[20:23], v[116:119], v[198:201], v[20:23]
	v_mfma_f32_16x16x32_bf16 v[24:27], v[72:75], v[194:197], v[24:27]
	v_mfma_f32_16x16x32_bf16 v[24:27], v[76:79], v[198:201], v[24:27]
	v_mfma_f32_16x16x32_bf16 v[16:19], v[152:155], v[194:197], v[16:19]
	v_mfma_f32_16x16x32_bf16 v[16:19], v[156:159], v[198:201], v[16:19]
	v_mfma_f32_16x16x32_bf16 v[12:15], v[64:67], v[202:205], v[12:15]
	v_mfma_f32_16x16x32_bf16 v[12:15], v[68:71], v[206:209], v[12:15]
	v_mfma_f32_16x16x32_bf16 v[4:7], v[80:83], v[202:205], v[4:7]
	v_mfma_f32_16x16x32_bf16 v[4:7], v[116:119], v[206:209], v[4:7]
	v_mfma_f32_16x16x32_bf16 v[8:11], v[72:75], v[202:205], v[8:11]
	v_mfma_f32_16x16x32_bf16 v[8:11], v[76:79], v[206:209], v[8:11]
	v_mfma_f32_16x16x32_bf16 v[0:3], v[152:155], v[202:205], v[0:3]
	v_mfma_f32_16x16x32_bf16 v[0:3], v[156:159], v[206:209], v[0:3]
	s_barrier
	s_add_i32 s88, s88, 2
	s_add_u32 s82, s82, 0x100
	s_addc_u32 s83, s83, 0
	s_add_u32 s75, s75, 0x100
	s_addc_u32 s81, s81, 0
	s_cmp_gt_u32 s88, 29
	s_cbranch_scc0 .LBB0_1190
	s_andn2_b64 vcc, s[18:19], s[4:5]
	s_and_b64 vcc, exec, vcc
	s_cbranch_vccz .LBB0_1193
	s_barrier
.LBB0_1193:
	s_lshl_b32 s23, s80, 8
	v_mbcnt_lo_u32_b32 v64, -1, 0
	v_mbcnt_hi_u32_b32 v64, -1, v64
	s_add_i32 s23, s23, s40
	v_and_b32_e32 v65, 15, v64
	v_or_b32_e32 v194, s23, v65
	s_lshl_b32 s23, s69, 7
	v_ashrrev_i32_e32 v64, 1, v64
	s_or_b32 s23, s23, s41
	v_and_b32_e32 v64, -8, v64
	v_or_b32_e32 v65, s40, v65
	v_add_u32_e32 v190, s23, v64
	v_add_u32_e32 v64, s41, v64
	v_lshl_add_u32 v65, v65, 3, s70
	s_add_i32 s70, s70, s57
	v_lshl_add_u32 v64, v64, 2, s70
	ds_read2_b64 v[172:175], v65 offset1:16
	ds_read2_b64 v[168:171], v65 offset0:32 offset1:48
	ds_read_b128 v[164:167], v64 offset:2048
	ds_read_b128 v[160:163], v64 offset:2064
	ds_read_b128 v[156:159], v64 offset:2560
	ds_read_b128 v[152:155], v64 offset:2576
	ds_read2_b64 v[116:119], v65 offset0:128 offset1:144
	ds_read2_b64 v[80:83], v65 offset0:160 offset1:176
	ds_read_b128 v[76:79], v64 offset:4096
	ds_read_b128 v[72:75], v64 offset:4112
	ds_read_b128 v[68:71], v64 offset:4608
	ds_read_b128 v[64:67], v64 offset:4624
	s_waitcnt lgkmcnt(0)
	v_ffbh_u32_e32 v195, v173
	v_min_u32_e32 v195, 32, v195
	v_lshlrev_b64 v[172:173], v195, v[172:173]
	v_min_u32_e32 v172, 1, v172
	v_or_b32_e32 v172, v173, v172
	v_cvt_f32_u32_e32 v172, v172
	v_sub_u32_e32 v173, 32, v195
	v_ashrrev_i32_e32 v191, 31, v190
	v_lshl_add_u64 v[190:191], v[190:191], 1, s[10:11]
	v_ldexp_f32 v172, v172, v173
	v_fmamk_f32 v172, v172, 0x32000000, v234
	v_rsq_f32_e32 v172, v172
	s_mov_b64 s[80:81], -1
	s_andn2_b64 vcc, exec, s[4:5]
	v_pk_fma_f32 v[150:151], v[150:151], v[172:173], v[166:167] op_sel_hi:[1,0,1]
	v_pk_fma_f32 v[148:149], v[148:149], v[172:173], v[164:165] op_sel_hi:[1,0,1]
	v_pk_fma_f32 v[146:147], v[146:147], v[172:173], v[162:163] op_sel_hi:[1,0,1]
	v_pk_fma_f32 v[144:145], v[144:145], v[172:173], v[160:161] op_sel_hi:[1,0,1]
	v_pk_fma_f32 v[142:143], v[142:143], v[172:173], v[158:159] op_sel_hi:[1,0,1]
	v_pk_fma_f32 v[140:141], v[140:141], v[172:173], v[156:157] op_sel_hi:[1,0,1]
	v_pk_fma_f32 v[138:139], v[138:139], v[172:173], v[154:155] op_sel_hi:[1,0,1]
	v_pk_fma_f32 v[136:137], v[136:137], v[172:173], v[152:153] op_sel_hi:[1,0,1]
	v_pk_mul_f32 v[172:173], v[150:151], s[50:51] op_sel_hi:[1,0]
	v_pk_mul_f32 v[196:197], v[148:149], s[50:51] op_sel_hi:[1,0]
	v_exp_f32_e32 v172, v172
	v_exp_f32_e32 v196, v196
	v_exp_f32_e32 v197, v197
	v_exp_f32_e32 v173, v173
	v_pk_add_f32 v[196:197], v[196:197], 1.0 op_sel_hi:[1,0]
	v_pk_add_f32 v[172:173], v[172:173], 1.0 op_sel_hi:[1,0]
	v_rcp_f32_e32 v196, v196
	v_rcp_f32_e32 v197, v197
	v_rcp_f32_e32 v172, v172
	v_rcp_f32_e32 v173, v173
	v_pk_mul_f32 v[148:149], v[148:149], v[196:197]
	s_nop 0
	v_pk_mul_f32 v[140:141], v[140:141], v[148:149]
	v_pk_mul_f32 v[150:151], v[150:151], v[172:173]
	v_pk_mul_f32 v[148:149], v[146:147], s[50:51] op_sel_hi:[1,0]
	v_pk_mul_f32 v[142:143], v[142:143], v[150:151]
	v_pk_mul_f32 v[150:151], v[144:145], s[50:51] op_sel_hi:[1,0]
	v_exp_f32_e32 v148, v148
	v_exp_f32_e32 v150, v150
	v_exp_f32_e32 v151, v151
	v_exp_f32_e32 v149, v149
	v_pk_add_f32 v[150:151], v[150:151], 1.0 op_sel_hi:[1,0]
	v_pk_add_f32 v[148:149], v[148:149], 1.0 op_sel_hi:[1,0]
	v_rcp_f32_e32 v150, v150
	v_rcp_f32_e32 v151, v151
	v_rcp_f32_e32 v148, v148
	v_rcp_f32_e32 v149, v149
	v_pk_mul_f32 v[144:145], v[144:145], v[150:151]
	v_pk_mul_f32 v[146:147], v[146:147], v[148:149]
	s_nop 0
	v_pk_mul_f32 v[146:147], v[138:139], v[146:147]
	v_pk_mul_f32 v[138:139], v[136:137], v[144:145]
	v_cvt_pk_bf16_f32 v136, v140, v141
	v_mad_i64_i32 v[140:141], s[70:71], v194, s25, v[190:191]
	v_cvt_pk_bf16_f32 v137, v142, v143
	v_cvt_pk_bf16_f32 v138, v138, v139
	v_cvt_pk_bf16_f32 v139, v146, v147
	global_store_dwordx4 v[140:141], v[136:139], off
	v_or_b32_e32 v140, 16, v194
	s_nop 0
	v_ffbh_u32_e32 v136, v175
	v_min_u32_e32 v138, 32, v136
	v_lshlrev_b64 v[136:137], v138, v[174:175]
	v_min_u32_e32 v136, 1, v136
	v_or_b32_e32 v136, v137, v136
	v_cvt_f32_u32_e32 v136, v136
	v_sub_u32_e32 v137, 32, v138
	v_ldexp_f32 v136, v136, v137
	v_fmamk_f32 v136, v136, 0x32000000, v234
	v_rsq_f32_e32 v136, v136
	s_nop 0
	v_pk_fma_f32 v[134:135], v[134:135], v[136:137], v[166:167] op_sel_hi:[1,0,1]
	v_pk_fma_f32 v[132:133], v[132:133], v[136:137], v[164:165] op_sel_hi:[1,0,1]
	v_pk_fma_f32 v[130:131], v[130:131], v[136:137], v[162:163] op_sel_hi:[1,0,1]
	v_pk_fma_f32 v[128:129], v[128:129], v[136:137], v[160:161] op_sel_hi:[1,0,1]
	v_pk_fma_f32 v[126:127], v[126:127], v[136:137], v[158:159] op_sel_hi:[1,0,1]
	v_pk_fma_f32 v[124:125], v[124:125], v[136:137], v[156:157] op_sel_hi:[1,0,1]
	v_pk_fma_f32 v[122:123], v[122:123], v[136:137], v[154:155] op_sel_hi:[1,0,1]
	v_pk_fma_f32 v[120:121], v[120:121], v[136:137], v[152:153] op_sel_hi:[1,0,1]
	v_pk_mul_f32 v[136:137], v[134:135], s[50:51] op_sel_hi:[1,0]
	v_pk_mul_f32 v[138:139], v[132:133], s[50:51] op_sel_hi:[1,0]
	v_exp_f32_e32 v136, v136
	v_exp_f32_e32 v138, v138
	v_exp_f32_e32 v139, v139
	v_exp_f32_e32 v137, v137
	v_pk_add_f32 v[138:139], v[138:139], 1.0 op_sel_hi:[1,0]
	v_pk_add_f32 v[136:137], v[136:137], 1.0 op_sel_hi:[1,0]
	v_rcp_f32_e32 v138, v138
	v_rcp_f32_e32 v139, v139
	v_rcp_f32_e32 v136, v136
	v_rcp_f32_e32 v137, v137
	v_pk_mul_f32 v[132:133], v[132:133], v[138:139]
	s_nop 0
	v_pk_mul_f32 v[124:125], v[124:125], v[132:133]
	v_pk_mul_f32 v[134:135], v[134:135], v[136:137]
	v_pk_mul_f32 v[132:133], v[130:131], s[50:51] op_sel_hi:[1,0]
	v_pk_mul_f32 v[126:127], v[126:127], v[134:135]
	v_pk_mul_f32 v[134:135], v[128:129], s[50:51] op_sel_hi:[1,0]
	v_exp_f32_e32 v132, v132
	v_exp_f32_e32 v134, v134
	v_exp_f32_e32 v135, v135
	v_exp_f32_e32 v133, v133
	v_pk_add_f32 v[134:135], v[134:135], 1.0 op_sel_hi:[1,0]
	v_pk_add_f32 v[132:133], v[132:133], 1.0 op_sel_hi:[1,0]
	v_rcp_f32_e32 v134, v134
	v_rcp_f32_e32 v135, v135
	v_rcp_f32_e32 v132, v132
	v_rcp_f32_e32 v133, v133
	v_pk_mul_f32 v[128:129], v[128:129], v[134:135]
	v_pk_mul_f32 v[130:131], v[130:131], v[132:133]
	s_nop 0
	v_pk_mul_f32 v[130:131], v[122:123], v[130:131]
	v_pk_mul_f32 v[122:123], v[120:121], v[128:129]
	v_cvt_pk_bf16_f32 v120, v124, v125
	v_mad_i64_i32 v[124:125], s[70:71], v140, s25, v[190:191]
	v_cvt_pk_bf16_f32 v121, v126, v127
	v_cvt_pk_bf16_f32 v122, v122, v123
	v_cvt_pk_bf16_f32 v123, v130, v131
	global_store_dwordx4 v[124:125], v[120:123], off
	v_or_b32_e32 v124, 32, v194
	s_nop 0
	v_ffbh_u32_e32 v120, v169
	v_min_u32_e32 v122, 32, v120
	v_lshlrev_b64 v[120:121], v122, v[168:169]
	v_min_u32_e32 v120, 1, v120
	v_or_b32_e32 v120, v121, v120
	v_cvt_f32_u32_e32 v120, v120
	v_sub_u32_e32 v121, 32, v122
	v_ldexp_f32 v120, v120, v121
	v_fmamk_f32 v120, v120, 0x32000000, v234
	v_rsq_f32_e32 v120, v120
	s_nop 0
	v_pk_fma_f32 v[114:115], v[114:115], v[120:121], v[166:167] op_sel_hi:[1,0,1]
	v_pk_fma_f32 v[112:113], v[112:113], v[120:121], v[164:165] op_sel_hi:[1,0,1]
	v_pk_fma_f32 v[110:111], v[110:111], v[120:121], v[162:163] op_sel_hi:[1,0,1]
	v_pk_fma_f32 v[108:109], v[108:109], v[120:121], v[160:161] op_sel_hi:[1,0,1]
	v_pk_fma_f32 v[106:107], v[106:107], v[120:121], v[158:159] op_sel_hi:[1,0,1]
	v_pk_fma_f32 v[104:105], v[104:105], v[120:121], v[156:157] op_sel_hi:[1,0,1]
	v_pk_fma_f32 v[102:103], v[102:103], v[120:121], v[154:155] op_sel_hi:[1,0,1]
	v_pk_fma_f32 v[100:101], v[100:101], v[120:121], v[152:153] op_sel_hi:[1,0,1]
	v_pk_mul_f32 v[120:121], v[114:115], s[50:51] op_sel_hi:[1,0]
	v_pk_mul_f32 v[122:123], v[112:113], s[50:51] op_sel_hi:[1,0]
	v_exp_f32_e32 v120, v120
	v_exp_f32_e32 v122, v122
	v_exp_f32_e32 v123, v123
	v_exp_f32_e32 v121, v121
	v_pk_add_f32 v[122:123], v[122:123], 1.0 op_sel_hi:[1,0]
	v_pk_add_f32 v[120:121], v[120:121], 1.0 op_sel_hi:[1,0]
	v_rcp_f32_e32 v122, v122
	v_rcp_f32_e32 v123, v123
	v_rcp_f32_e32 v120, v120
	v_rcp_f32_e32 v121, v121
	v_pk_mul_f32 v[112:113], v[112:113], v[122:123]
	s_nop 0
	v_pk_mul_f32 v[104:105], v[104:105], v[112:113]
	v_pk_mul_f32 v[114:115], v[114:115], v[120:121]
	v_pk_mul_f32 v[112:113], v[110:111], s[50:51] op_sel_hi:[1,0]
	v_pk_mul_f32 v[106:107], v[106:107], v[114:115]
	v_pk_mul_f32 v[114:115], v[108:109], s[50:51] op_sel_hi:[1,0]
	v_exp_f32_e32 v112, v112
	v_exp_f32_e32 v114, v114
	v_exp_f32_e32 v115, v115
	v_exp_f32_e32 v113, v113
	v_pk_add_f32 v[114:115], v[114:115], 1.0 op_sel_hi:[1,0]
	v_pk_add_f32 v[112:113], v[112:113], 1.0 op_sel_hi:[1,0]
	v_rcp_f32_e32 v114, v114
	v_rcp_f32_e32 v115, v115
	v_rcp_f32_e32 v112, v112
	v_rcp_f32_e32 v113, v113
	v_pk_mul_f32 v[108:109], v[108:109], v[114:115]
	v_pk_mul_f32 v[110:111], v[110:111], v[112:113]
	s_nop 0
	v_pk_mul_f32 v[110:111], v[102:103], v[110:111]
	v_pk_mul_f32 v[102:103], v[100:101], v[108:109]
	v_cvt_pk_bf16_f32 v100, v104, v105
	v_mad_i64_i32 v[104:105], s[70:71], v124, s25, v[190:191]
	v_cvt_pk_bf16_f32 v101, v106, v107
	v_cvt_pk_bf16_f32 v102, v102, v103
	v_cvt_pk_bf16_f32 v103, v110, v111
	global_store_dwordx4 v[104:105], v[100:103], off
	v_or_b32_e32 v104, 48, v194
	s_nop 0
	v_ffbh_u32_e32 v100, v171
	v_min_u32_e32 v102, 32, v100
	v_lshlrev_b64 v[100:101], v102, v[170:171]
	v_min_u32_e32 v100, 1, v100
	v_or_b32_e32 v100, v101, v100
	v_cvt_f32_u32_e32 v100, v100
	v_sub_u32_e32 v101, 32, v102
	v_ldexp_f32 v100, v100, v101
	v_fmamk_f32 v100, v100, 0x32000000, v234
	v_rsq_f32_e32 v100, v100
	s_nop 0
	v_pk_fma_f32 v[98:99], v[98:99], v[100:101], v[166:167] op_sel_hi:[1,0,1]
	v_pk_fma_f32 v[96:97], v[96:97], v[100:101], v[164:165] op_sel_hi:[1,0,1]
	v_pk_fma_f32 v[94:95], v[94:95], v[100:101], v[162:163] op_sel_hi:[1,0,1]
	v_pk_fma_f32 v[92:93], v[92:93], v[100:101], v[160:161] op_sel_hi:[1,0,1]
	v_pk_fma_f32 v[90:91], v[90:91], v[100:101], v[158:159] op_sel_hi:[1,0,1]
	v_pk_fma_f32 v[88:89], v[88:89], v[100:101], v[156:157] op_sel_hi:[1,0,1]
	v_pk_fma_f32 v[86:87], v[86:87], v[100:101], v[154:155] op_sel_hi:[1,0,1]
	v_pk_fma_f32 v[84:85], v[84:85], v[100:101], v[152:153] op_sel_hi:[1,0,1]
	v_pk_mul_f32 v[100:101], v[98:99], s[50:51] op_sel_hi:[1,0]
	v_pk_mul_f32 v[102:103], v[96:97], s[50:51] op_sel_hi:[1,0]
	v_exp_f32_e32 v100, v100
	v_exp_f32_e32 v102, v102
	v_exp_f32_e32 v103, v103
	v_exp_f32_e32 v101, v101
	v_pk_add_f32 v[102:103], v[102:103], 1.0 op_sel_hi:[1,0]
	v_pk_add_f32 v[100:101], v[100:101], 1.0 op_sel_hi:[1,0]
	v_rcp_f32_e32 v102, v102
	v_rcp_f32_e32 v103, v103
	v_rcp_f32_e32 v100, v100
	v_rcp_f32_e32 v101, v101
	v_pk_mul_f32 v[96:97], v[96:97], v[102:103]
	s_nop 0
	v_pk_mul_f32 v[88:89], v[88:89], v[96:97]
	v_pk_mul_f32 v[98:99], v[98:99], v[100:101]
	v_pk_mul_f32 v[96:97], v[94:95], s[50:51] op_sel_hi:[1,0]
	v_pk_mul_f32 v[90:91], v[90:91], v[98:99]
	v_pk_mul_f32 v[98:99], v[92:93], s[50:51] op_sel_hi:[1,0]
	v_exp_f32_e32 v96, v96
	v_exp_f32_e32 v98, v98
	v_exp_f32_e32 v99, v99
	v_exp_f32_e32 v97, v97
	v_pk_add_f32 v[98:99], v[98:99], 1.0 op_sel_hi:[1,0]
	v_pk_add_f32 v[96:97], v[96:97], 1.0 op_sel_hi:[1,0]
	v_rcp_f32_e32 v98, v98
	v_rcp_f32_e32 v99, v99
	v_rcp_f32_e32 v96, v96
	v_rcp_f32_e32 v97, v97
	v_pk_mul_f32 v[92:93], v[92:93], v[98:99]
	v_pk_mul_f32 v[94:95], v[94:95], v[96:97]
	s_nop 0
	v_pk_mul_f32 v[94:95], v[86:87], v[94:95]
	v_pk_mul_f32 v[86:87], v[84:85], v[92:93]
	v_cvt_pk_bf16_f32 v84, v88, v89
	v_mad_i64_i32 v[88:89], s[70:71], v104, s25, v[190:191]
	v_cvt_pk_bf16_f32 v85, v90, v91
	v_cvt_pk_bf16_f32 v86, v86, v87
	v_cvt_pk_bf16_f32 v87, v94, v95
	global_store_dwordx4 v[88:89], v[84:87], off
	v_add_u32_e32 v88, 0x80, v194
	s_nop 0
	v_ffbh_u32_e32 v84, v117
	v_min_u32_e32 v86, 32, v84
	v_lshlrev_b64 v[84:85], v86, v[116:117]
	v_min_u32_e32 v84, 1, v84
	v_or_b32_e32 v84, v85, v84
	v_cvt_f32_u32_e32 v84, v84
	v_sub_u32_e32 v85, 32, v86
	v_ldexp_f32 v84, v84, v85
	v_fmamk_f32 v84, v84, 0x32000000, v234
	v_rsq_f32_e32 v84, v84
	s_nop 0
	v_pk_fma_f32 v[62:63], v[62:63], v[84:85], v[78:79] op_sel_hi:[1,0,1]
	v_pk_fma_f32 v[60:61], v[60:61], v[84:85], v[76:77] op_sel_hi:[1,0,1]
	v_pk_fma_f32 v[58:59], v[58:59], v[84:85], v[74:75] op_sel_hi:[1,0,1]
	v_pk_fma_f32 v[56:57], v[56:57], v[84:85], v[72:73] op_sel_hi:[1,0,1]
	v_pk_fma_f32 v[54:55], v[54:55], v[84:85], v[70:71] op_sel_hi:[1,0,1]
	v_pk_fma_f32 v[52:53], v[52:53], v[84:85], v[68:69] op_sel_hi:[1,0,1]
	v_pk_fma_f32 v[50:51], v[50:51], v[84:85], v[66:67] op_sel_hi:[1,0,1]
	v_pk_fma_f32 v[48:49], v[48:49], v[84:85], v[64:65] op_sel_hi:[1,0,1]
	v_pk_mul_f32 v[84:85], v[62:63], s[50:51] op_sel_hi:[1,0]
	v_pk_mul_f32 v[86:87], v[60:61], s[50:51] op_sel_hi:[1,0]
	v_exp_f32_e32 v84, v84
	v_exp_f32_e32 v86, v86
	v_exp_f32_e32 v87, v87
	v_exp_f32_e32 v85, v85
	v_pk_add_f32 v[86:87], v[86:87], 1.0 op_sel_hi:[1,0]
	v_pk_add_f32 v[84:85], v[84:85], 1.0 op_sel_hi:[1,0]
	v_rcp_f32_e32 v86, v86
	v_rcp_f32_e32 v87, v87
	v_rcp_f32_e32 v84, v84
	v_rcp_f32_e32 v85, v85
	v_pk_mul_f32 v[60:61], v[60:61], v[86:87]
	s_nop 0
	v_pk_mul_f32 v[52:53], v[52:53], v[60:61]
	v_pk_mul_f32 v[62:63], v[62:63], v[84:85]
	v_pk_mul_f32 v[60:61], v[58:59], s[50:51] op_sel_hi:[1,0]
	v_pk_mul_f32 v[54:55], v[54:55], v[62:63]
	v_pk_mul_f32 v[62:63], v[56:57], s[50:51] op_sel_hi:[1,0]
	v_exp_f32_e32 v60, v60
	v_exp_f32_e32 v62, v62
	v_exp_f32_e32 v63, v63
	v_exp_f32_e32 v61, v61
	v_pk_add_f32 v[62:63], v[62:63], 1.0 op_sel_hi:[1,0]
	v_pk_add_f32 v[60:61], v[60:61], 1.0 op_sel_hi:[1,0]
	v_rcp_f32_e32 v62, v62
	v_rcp_f32_e32 v63, v63
	v_rcp_f32_e32 v60, v60
	v_rcp_f32_e32 v61, v61
	v_pk_mul_f32 v[56:57], v[56:57], v[62:63]
	v_pk_mul_f32 v[58:59], v[58:59], v[60:61]
	s_nop 0
	v_pk_mul_f32 v[58:59], v[50:51], v[58:59]
	v_pk_mul_f32 v[50:51], v[48:49], v[56:57]
	v_cvt_pk_bf16_f32 v48, v52, v53
	v_mad_i64_i32 v[52:53], s[70:71], v88, s25, v[190:191]
	v_cvt_pk_bf16_f32 v49, v54, v55
	v_cvt_pk_bf16_f32 v50, v50, v51
	v_cvt_pk_bf16_f32 v51, v58, v59
	global_store_dwordx4 v[52:53], v[48:51], off
	v_add_u32_e32 v52, 0x90, v194
	s_nop 0
	v_ffbh_u32_e32 v48, v119
	v_min_u32_e32 v50, 32, v48
	v_lshlrev_b64 v[48:49], v50, v[118:119]
	v_min_u32_e32 v48, 1, v48
	v_or_b32_e32 v48, v49, v48
	v_cvt_f32_u32_e32 v48, v48
	v_sub_u32_e32 v49, 32, v50
	v_ldexp_f32 v48, v48, v49
	v_fmamk_f32 v48, v48, 0x32000000, v234
	v_rsq_f32_e32 v48, v48
	s_nop 0
	v_pk_fma_f32 v[46:47], v[46:47], v[48:49], v[78:79] op_sel_hi:[1,0,1]
	v_pk_fma_f32 v[44:45], v[44:45], v[48:49], v[76:77] op_sel_hi:[1,0,1]
	v_pk_fma_f32 v[42:43], v[42:43], v[48:49], v[74:75] op_sel_hi:[1,0,1]
	v_pk_fma_f32 v[40:41], v[40:41], v[48:49], v[72:73] op_sel_hi:[1,0,1]
	v_pk_fma_f32 v[38:39], v[38:39], v[48:49], v[70:71] op_sel_hi:[1,0,1]
	v_pk_fma_f32 v[36:37], v[36:37], v[48:49], v[68:69] op_sel_hi:[1,0,1]
	v_pk_fma_f32 v[34:35], v[34:35], v[48:49], v[66:67] op_sel_hi:[1,0,1]
	v_pk_fma_f32 v[32:33], v[32:33], v[48:49], v[64:65] op_sel_hi:[1,0,1]
	v_pk_mul_f32 v[48:49], v[46:47], s[50:51] op_sel_hi:[1,0]
	v_pk_mul_f32 v[50:51], v[44:45], s[50:51] op_sel_hi:[1,0]
	v_exp_f32_e32 v48, v48
	v_exp_f32_e32 v50, v50
	v_exp_f32_e32 v51, v51
	v_exp_f32_e32 v49, v49
	v_pk_add_f32 v[50:51], v[50:51], 1.0 op_sel_hi:[1,0]
	v_pk_add_f32 v[48:49], v[48:49], 1.0 op_sel_hi:[1,0]
	v_rcp_f32_e32 v50, v50
	v_rcp_f32_e32 v51, v51
	v_rcp_f32_e32 v48, v48
	v_rcp_f32_e32 v49, v49
	v_pk_mul_f32 v[44:45], v[44:45], v[50:51]
	s_nop 0
	v_pk_mul_f32 v[36:37], v[36:37], v[44:45]
	v_pk_mul_f32 v[46:47], v[46:47], v[48:49]
	v_pk_mul_f32 v[44:45], v[42:43], s[50:51] op_sel_hi:[1,0]
	v_pk_mul_f32 v[38:39], v[38:39], v[46:47]
	v_pk_mul_f32 v[46:47], v[40:41], s[50:51] op_sel_hi:[1,0]
	v_exp_f32_e32 v44, v44
	v_exp_f32_e32 v46, v46
	v_exp_f32_e32 v47, v47
	v_exp_f32_e32 v45, v45
	v_pk_add_f32 v[46:47], v[46:47], 1.0 op_sel_hi:[1,0]
	v_pk_add_f32 v[44:45], v[44:45], 1.0 op_sel_hi:[1,0]
	v_rcp_f32_e32 v46, v46
	v_rcp_f32_e32 v47, v47
	v_rcp_f32_e32 v44, v44
	v_rcp_f32_e32 v45, v45
	v_pk_mul_f32 v[40:41], v[40:41], v[46:47]
	v_pk_mul_f32 v[42:43], v[42:43], v[44:45]
	s_nop 0
	v_pk_mul_f32 v[42:43], v[34:35], v[42:43]
	v_pk_mul_f32 v[34:35], v[32:33], v[40:41]
	v_cvt_pk_bf16_f32 v32, v36, v37
	v_mad_i64_i32 v[36:37], s[70:71], v52, s25, v[190:191]
	v_cvt_pk_bf16_f32 v33, v38, v39
	v_cvt_pk_bf16_f32 v34, v34, v35
	v_cvt_pk_bf16_f32 v35, v42, v43
	global_store_dwordx4 v[36:37], v[32:35], off
	v_add_u32_e32 v36, 0xa0, v194
	s_nop 0
	v_ffbh_u32_e32 v32, v81
	v_min_u32_e32 v34, 32, v32
	v_lshlrev_b64 v[32:33], v34, v[80:81]
	v_min_u32_e32 v32, 1, v32
	v_or_b32_e32 v32, v33, v32
	v_cvt_f32_u32_e32 v32, v32
	v_sub_u32_e32 v33, 32, v34
	v_ldexp_f32 v32, v32, v33
	v_fmamk_f32 v32, v32, 0x32000000, v234
	v_rsq_f32_e32 v32, v32
	s_nop 0
	v_pk_fma_f32 v[30:31], v[30:31], v[32:33], v[78:79] op_sel_hi:[1,0,1]
	v_pk_fma_f32 v[28:29], v[28:29], v[32:33], v[76:77] op_sel_hi:[1,0,1]
	v_pk_fma_f32 v[26:27], v[26:27], v[32:33], v[74:75] op_sel_hi:[1,0,1]
	v_pk_fma_f32 v[24:25], v[24:25], v[32:33], v[72:73] op_sel_hi:[1,0,1]
	v_pk_fma_f32 v[22:23], v[22:23], v[32:33], v[70:71] op_sel_hi:[1,0,1]
	v_pk_fma_f32 v[20:21], v[20:21], v[32:33], v[68:69] op_sel_hi:[1,0,1]
	v_pk_fma_f32 v[18:19], v[18:19], v[32:33], v[66:67] op_sel_hi:[1,0,1]
	v_pk_fma_f32 v[16:17], v[16:17], v[32:33], v[64:65] op_sel_hi:[1,0,1]
	v_pk_mul_f32 v[32:33], v[30:31], s[50:51] op_sel_hi:[1,0]
	v_pk_mul_f32 v[34:35], v[28:29], s[50:51] op_sel_hi:[1,0]
	v_exp_f32_e32 v32, v32
	v_exp_f32_e32 v34, v34
	v_exp_f32_e32 v35, v35
	v_exp_f32_e32 v33, v33
	v_pk_add_f32 v[34:35], v[34:35], 1.0 op_sel_hi:[1,0]
	v_pk_add_f32 v[32:33], v[32:33], 1.0 op_sel_hi:[1,0]
	v_rcp_f32_e32 v34, v34
	v_rcp_f32_e32 v35, v35
	v_rcp_f32_e32 v32, v32
	v_rcp_f32_e32 v33, v33
	v_pk_mul_f32 v[28:29], v[28:29], v[34:35]
	s_nop 0
	v_pk_mul_f32 v[20:21], v[20:21], v[28:29]
	v_pk_mul_f32 v[30:31], v[30:31], v[32:33]
	v_pk_mul_f32 v[28:29], v[26:27], s[50:51] op_sel_hi:[1,0]
	v_pk_mul_f32 v[22:23], v[22:23], v[30:31]
	v_pk_mul_f32 v[30:31], v[24:25], s[50:51] op_sel_hi:[1,0]
	v_exp_f32_e32 v28, v28
	v_exp_f32_e32 v30, v30
	v_exp_f32_e32 v31, v31
	v_exp_f32_e32 v29, v29
	v_pk_add_f32 v[30:31], v[30:31], 1.0 op_sel_hi:[1,0]
	v_pk_add_f32 v[28:29], v[28:29], 1.0 op_sel_hi:[1,0]
	v_rcp_f32_e32 v30, v30
	v_rcp_f32_e32 v31, v31
	v_rcp_f32_e32 v28, v28
	v_rcp_f32_e32 v29, v29
	v_pk_mul_f32 v[24:25], v[24:25], v[30:31]
	v_pk_mul_f32 v[26:27], v[26:27], v[28:29]
	s_nop 0
	v_pk_mul_f32 v[26:27], v[18:19], v[26:27]
	v_pk_mul_f32 v[18:19], v[16:17], v[24:25]
	v_cvt_pk_bf16_f32 v16, v20, v21
	v_mad_i64_i32 v[20:21], s[70:71], v36, s25, v[190:191]
	v_cvt_pk_bf16_f32 v17, v22, v23
	v_cvt_pk_bf16_f32 v18, v18, v19
	v_cvt_pk_bf16_f32 v19, v26, v27
	global_store_dwordx4 v[20:21], v[16:19], off
	v_add_u32_e32 v20, 0xb0, v194
	s_nop 0
	v_ffbh_u32_e32 v16, v83
	v_min_u32_e32 v18, 32, v16
	v_lshlrev_b64 v[16:17], v18, v[82:83]
	v_min_u32_e32 v16, 1, v16
	v_or_b32_e32 v16, v17, v16
	v_cvt_f32_u32_e32 v16, v16
	v_sub_u32_e32 v17, 32, v18
	v_ldexp_f32 v16, v16, v17
	v_fmamk_f32 v16, v16, 0x32000000, v234
	v_rsq_f32_e32 v16, v16
	s_nop 0
	v_pk_fma_f32 v[14:15], v[14:15], v[16:17], v[78:79] op_sel_hi:[1,0,1]
	v_pk_fma_f32 v[12:13], v[12:13], v[16:17], v[76:77] op_sel_hi:[1,0,1]
	v_pk_fma_f32 v[10:11], v[10:11], v[16:17], v[74:75] op_sel_hi:[1,0,1]
	v_pk_fma_f32 v[8:9], v[8:9], v[16:17], v[72:73] op_sel_hi:[1,0,1]
	v_pk_fma_f32 v[6:7], v[6:7], v[16:17], v[70:71] op_sel_hi:[1,0,1]
	v_pk_fma_f32 v[4:5], v[4:5], v[16:17], v[68:69] op_sel_hi:[1,0,1]
	v_pk_fma_f32 v[2:3], v[2:3], v[16:17], v[66:67] op_sel_hi:[1,0,1]
	v_pk_fma_f32 v[0:1], v[0:1], v[16:17], v[64:65] op_sel_hi:[1,0,1]
	v_pk_mul_f32 v[16:17], v[14:15], s[50:51] op_sel_hi:[1,0]
	v_pk_mul_f32 v[18:19], v[12:13], s[50:51] op_sel_hi:[1,0]
	v_exp_f32_e32 v16, v16
	v_exp_f32_e32 v18, v18
	v_exp_f32_e32 v19, v19
	v_exp_f32_e32 v17, v17
	v_pk_add_f32 v[18:19], v[18:19], 1.0 op_sel_hi:[1,0]
	v_pk_add_f32 v[16:17], v[16:17], 1.0 op_sel_hi:[1,0]
	v_rcp_f32_e32 v18, v18
	v_rcp_f32_e32 v19, v19
	v_rcp_f32_e32 v16, v16
	v_rcp_f32_e32 v17, v17
	v_pk_mul_f32 v[12:13], v[12:13], v[18:19]
	s_nop 0
	v_pk_mul_f32 v[4:5], v[4:5], v[12:13]
	v_pk_mul_f32 v[14:15], v[14:15], v[16:17]
	v_pk_mul_f32 v[12:13], v[10:11], s[50:51] op_sel_hi:[1,0]
	v_pk_mul_f32 v[6:7], v[6:7], v[14:15]
	v_pk_mul_f32 v[14:15], v[8:9], s[50:51] op_sel_hi:[1,0]
	v_exp_f32_e32 v12, v12
	v_exp_f32_e32 v14, v14
	v_exp_f32_e32 v15, v15
	v_exp_f32_e32 v13, v13
	v_pk_add_f32 v[14:15], v[14:15], 1.0 op_sel_hi:[1,0]
	v_pk_add_f32 v[12:13], v[12:13], 1.0 op_sel_hi:[1,0]
	v_rcp_f32_e32 v14, v14
	v_rcp_f32_e32 v15, v15
	v_rcp_f32_e32 v12, v12
	v_rcp_f32_e32 v13, v13
	v_pk_mul_f32 v[8:9], v[8:9], v[14:15]
	v_pk_mul_f32 v[10:11], v[10:11], v[12:13]
	s_nop 0
	v_pk_mul_f32 v[10:11], v[2:3], v[10:11]
	v_pk_mul_f32 v[2:3], v[0:1], v[8:9]
	v_cvt_pk_bf16_f32 v0, v4, v5
	v_mad_i64_i32 v[4:5], s[70:71], v20, s25, v[190:191]
	v_cvt_pk_bf16_f32 v1, v6, v7
	v_cvt_pk_bf16_f32 v2, v2, v3
	v_cvt_pk_bf16_f32 v3, v10, v11
	global_store_dwordx4 v[4:5], v[0:3], off
	s_cbranch_vccnz .LBB0_1178
	s_branch .LBB0_1177
